# strategy 4: static s_setprio 1 for waves 4-7 during the prep / chunk-output / merge phases
# speedup vs baseline: 1.0009x; 1.0009x over previous
; __global__ void __launch_bounds__(NT) mega(P p) {
;     ...
;     for (int u = blockIdx.x; u < SB_M1 + 3 * NUNIT; u += gridDim.x) {
;       if (u < SB_M1) sb_unit(p, u, smem);
;       else {
;         const int v = u - SB_M1, kind = v / NUNIT, uu = v % NUNIT;
;         if (kind == 0) gla_prep_unit(p, layer, uu, smem);
;         else if (kind == 1) ml_prep_unit(p, layer, uu, smem);
;         else ret_prep_unit(p, layer, uu, smem);
;       }
;     }
.LBB0_202:
	s_or_b64 exec, exec, s[0:1]
	v_readlane_b32 s0, v254, 42
	v_readlane_b32 s1, v254, 43
	s_andn2_b64 vcc, exec, s[0:1]
	s_waitcnt lgkmcnt(0)
	s_barrier
	v_readfirstlane_b32 s32, v136
	s_nop 0
	s_cmpk_ge_u32 s32, 0x100
	s_cbranch_scc0 .Lprio_0
	s_setprio 1
.Lprio_0:
	s_cbranch_vccnz .LBB0_312
	v_readlane_b32 s1, v254, 61
	v_readlane_b32 s56, v254, 25
	v_readlane_b32 s12, v254, 8
	s_lshl_b32 s2, s1, 2
	s_lshl_b32 s0, s1, 13
	v_readlane_b32 s58, v254, 27
	v_readlane_b32 s60, v254, 29
	v_readlane_b32 s13, v254, 9
	v_readlane_b32 s14, v254, 10
	v_readlane_b32 s15, v254, 11
	v_readlane_b32 s16, v254, 12
	v_readlane_b32 s17, v254, 13
	v_readlane_b32 s18, v254, 14
	v_readlane_b32 s19, v254, 15
	v_readlane_b32 s20, v254, 16
	v_readlane_b32 s21, v254, 17
	v_readlane_b32 s22, v254, 18
	v_readlane_b32 s23, v254, 19
	v_readlane_b32 s61, v254, 30
	s_add_u32 s58, s60, s0
	v_readlane_b32 s24, v254, 20
	v_readlane_b32 s25, v254, 21
	v_readlane_b32 s26, v254, 22
	v_readlane_b32 s27, v254, 23
	s_mov_b64 s[12:13], s[16:17]
	v_readlane_b32 s62, v254, 31
	s_addc_u32 s60, s61, 0
	s_mov_b64 s[14:15], s[18:19]
	s_mov_b64 s[16:17], s[20:21]
	s_mov_b64 s[18:19], s[22:23]
	s_mov_b64 s[20:21], s[24:25]
	s_mov_b64 s[22:23], s[26:27]
	v_readlane_b32 s63, v254, 32
	s_add_u32 s62, s22, s0
	s_addc_u32 s63, s23, 0
	s_lshl_b32 s96, s1, 7
	s_lshl_b64 s[0:1], s[96:97], 2
	v_readlane_b32 s57, v254, 26
	v_readlane_b32 s66, v254, 35
	v_readlane_b32 s68, v254, 37
	s_add_u32 s56, s56, s0
	s_addc_u32 s66, s57, s1
	s_mov_b32 s57, s2
	s_mov_b32 s68, s53
	v_readlane_b32 s59, v254, 28
	v_readlane_b32 s64, v254, 33
	v_readlane_b32 s65, v254, 34
	v_readlane_b32 s67, v254, 36
	v_readlane_b32 s69, v254, 38
	v_readlane_b32 s70, v254, 39
	v_readlane_b32 s71, v254, 40
	s_branch .LBB0_207

;   __device__ __forceinline__ unsigned* bar() const { unsigned o_ = (unsigned)(OFF_bar); asm volatile("" : "+s"(o_)); return (unsigned*)(ws + o_); }
; __device__ __forceinline__ unsigned xb_ld(unsigned* p)              { return __hip_atomic_load(p, __ATOMIC_RELAXED, __HIP_MEMORY_SCOPE_AGENT); }
; __device__ __forceinline__ unsigned xb_add(unsigned* p, unsigned v) { return __hip_atomic_fetch_add(p, v, __ATOMIC_RELAXED, __HIP_MEMORY_SCOPE_AGENT); }
; #define XB_SPIN(cond, bar) do { unsigned _sp = 0; while (cond) { __builtin_amdgcn_s_sleep(1); \
;     if ((++_sp & 255u) == 0u) { if (xb_ld(&(bar)[XB_TMO])) break; if (_sp > XB_SPIN_CAP) { atomicAdd(&(bar)[XB_TMO], 1u); break; } } } } while (0)
; __device__ __forceinline__ void xcd_barrier(const XcdBarrier& b) {
;     asm volatile("s_waitcnt vmcnt(0)" ::: "memory");
;     __syncthreads();
;     if (threadIdx.x == 0) {
;         unsigned* bar = b.bar;
;         __builtin_amdgcn_s_waitcnt(0);
;         unsigned nloc = b.st[0], nx = b.st[1];
;         if (nloc == 0u) { xcd_barrier_complete(bar, b.x, nloc, nx); b.st[0] = nloc; b.st[1] = nx; }
;         const unsigned old = xb_add(&bar[XB_XSUB(b.x)], 1u);
;         const unsigned gen = old / nloc;
;         if (old + 1u == (gen + 1u) * nloc) {
;             __builtin_amdgcn_fence(__ATOMIC_RELEASE, "agent");
;             asm volatile("s_waitcnt vmcnt(0)" ::: "memory");
;             const unsigned og = xb_add(&bar[XB_TOP], 1u);
;             const unsigned tg = og / nx;
;             if (og + 1u == (tg + 1u) * nx) xb_add(&bar[XB_TOPGEN], 1u);
;             else XB_SPIN(xb_ld(&bar[XB_TOPGEN]) == tg, bar);
;             __builtin_amdgcn_fence(__ATOMIC_ACQUIRE, "agent");
;             xb_add(&bar[XB_XGEN(b.x)], 1u);
;             asm volatile("s_waitcnt vmcnt(0)" ::: "memory");
;         } else {
;             XB_SPIN(xb_ld(&bar[XB_XGEN(b.x)]) == gen, bar);
;             __builtin_amdgcn_fence(__ATOMIC_ACQUIRE, "agent");
;             asm volatile("s_waitcnt vmcnt(0)" ::: "memory");
;         }
;     }
;     __syncthreads();
; }
.LBB0_312:
	s_setprio 0
	s_mov_b32 s2, 0x1c230700
	s_getreg_b32 s4, hwreg(HW_REG_XCC_ID, 0, 4)
	s_waitcnt vmcnt(0)
	v_readlane_b32 s82, v255, 2
	v_readlane_b32 s83, v255, 3
	s_barrier
	s_and_saveexec_b64 s[0:1], s[82:83]
	s_mov_b32 s11, 0x20000
	s_cbranch_execz .LBB0_364
	v_readlane_b32 s3, v254, 55
	s_waitcnt vmcnt(0) expcnt(0) lgkmcnt(0)
	s_add_u32 s2, s76, s2
	v_mov_b32_e32 v0, s3
	ds_read_b32 v2, v0
	v_readlane_b32 s3, v254, 56
	s_waitcnt lgkmcnt(0)
	v_cmp_ne_u32_e32 vcc, 0, v2
	v_mov_b32_e32 v0, s3
	ds_read_b32 v0, v0
	s_addc_u32 s3, s77, 0
	s_and_b32 s20, s4, 15
	s_cbranch_vccnz .LBB0_328
	s_add_u32 s4, s2, 0x1000
	s_addc_u32 s5, s3, 0
	s_add_u32 s6, s2, 0x1100
	s_addc_u32 s7, s3, 0
	s_add_u32 s8, s2, 0x1200
	s_addc_u32 s9, s3, 0
	s_add_u32 s12, s2, 0x1300
	s_addc_u32 s13, s3, 0
	s_mov_b32 s21, 1
	s_branch .LBB0_316

; __global__ void __launch_bounds__(NT) mega(P p) {
;     ...
;     for (int u = blockIdx.x; u < 3 * NUNIT + (NUNIT - SB_M1); u += gridDim.x) {
;       if (u >= 3 * NUNIT) { sb_unit(p, SB_M1 + (u - 3 * NUNIT), smem); continue; }
;       const int kind = u / NUNIT, uu = u % NUNIT;
;       if (kind == 0) out_unit<0>(p, layer, uu, smem);
;       else if (kind == 1) out_unit<1>(p, layer, uu, smem);
;       else out_unit<2>(p, layer, uu, smem);
;     }
.LBB0_481:
	s_or_b64 exec, exec, s[0:1]
	v_readlane_b32 s0, v254, 44
	v_readlane_b32 s1, v254, 45
	s_andn2_b64 vcc, exec, s[0:1]
	s_waitcnt lgkmcnt(0)
	s_barrier
	v_readfirstlane_b32 s32, v136
	s_nop 0
	s_cmpk_ge_u32 s32, 0x100
	s_cbranch_scc0 .Lprio_1
	s_setprio 1
.Lprio_1:
	s_cbranch_vccnz .LBB0_673
	v_readlane_b32 s0, v254, 61
	s_lshl_b32 s96, s0, 8
	v_readlane_b32 s12, v254, 25
	s_lshl_b64 s[0:1], s[96:97], 2
	v_readlane_b32 s24, v254, 37
	v_readlane_b32 s25, v254, 38
	s_add_u32 s60, s24, s0
	v_readlane_b32 s22, v254, 35
	s_addc_u32 s62, s25, s1
	v_readlane_b32 s23, v254, 36
	s_add_u32 s63, s22, s0
	v_readlane_b32 s14, v254, 27
	s_addc_u32 s64, s23, s1
	v_readlane_b32 s15, v254, 28
	s_add_u32 s65, s14, s0
	s_addc_u32 s66, s15, s1
	s_nop 0
	s_mul_i32 s33, s53, 7
	s_add_i32 s68, s53, 0x538
	s_cmpk_lt_i32 s33, 0x618
	s_cselect_b32 s33, s33, s68
	s_add_i32 s68, s33, 0xfffffbd0
	s_mov_b32 s58, 0
	v_readlane_b32 s13, v254, 26
	v_readlane_b32 s16, v254, 29
	v_readlane_b32 s17, v254, 30
	v_readlane_b32 s18, v254, 31
	v_readlane_b32 s19, v254, 32
	v_readlane_b32 s20, v254, 33
	v_readlane_b32 s21, v254, 34
	v_readlane_b32 s26, v254, 39
	v_readlane_b32 s27, v254, 40
	s_branch .LBB0_485

;   __device__ __forceinline__ unsigned* bar() const { unsigned o_ = (unsigned)(OFF_bar); asm volatile("" : "+s"(o_)); return (unsigned*)(ws + o_); }
; __device__ __forceinline__ unsigned xb_ld(unsigned* p)              { return __hip_atomic_load(p, __ATOMIC_RELAXED, __HIP_MEMORY_SCOPE_AGENT); }
; __device__ __forceinline__ unsigned xb_add(unsigned* p, unsigned v) { return __hip_atomic_fetch_add(p, v, __ATOMIC_RELAXED, __HIP_MEMORY_SCOPE_AGENT); }
; #define XB_SPIN(cond, bar) do { unsigned _sp = 0; while (cond) { __builtin_amdgcn_s_sleep(1); \
;     if ((++_sp & 255u) == 0u) { if (xb_ld(&(bar)[XB_TMO])) break; if (_sp > XB_SPIN_CAP) { atomicAdd(&(bar)[XB_TMO], 1u); break; } } } } while (0)
; __device__ __forceinline__ void xcd_barrier(const XcdBarrier& b) {
;     asm volatile("s_waitcnt vmcnt(0)" ::: "memory");
;     __syncthreads();
;     if (threadIdx.x == 0) {
;         unsigned* bar = b.bar;
;         __builtin_amdgcn_s_waitcnt(0);
;         unsigned nloc = b.st[0], nx = b.st[1];
;         if (nloc == 0u) { xcd_barrier_complete(bar, b.x, nloc, nx); b.st[0] = nloc; b.st[1] = nx; }
;         const unsigned old = xb_add(&bar[XB_XSUB(b.x)], 1u);
;         const unsigned gen = old / nloc;
;         if (old + 1u == (gen + 1u) * nloc) {
;             __builtin_amdgcn_fence(__ATOMIC_RELEASE, "agent");
;             asm volatile("s_waitcnt vmcnt(0)" ::: "memory");
;             const unsigned og = xb_add(&bar[XB_TOP], 1u);
;             const unsigned tg = og / nx;
;             if (og + 1u == (tg + 1u) * nx) xb_add(&bar[XB_TOPGEN], 1u);
;             else XB_SPIN(xb_ld(&bar[XB_TOPGEN]) == tg, bar);
;             __builtin_amdgcn_fence(__ATOMIC_ACQUIRE, "agent");
;             xb_add(&bar[XB_XGEN(b.x)], 1u);
;             asm volatile("s_waitcnt vmcnt(0)" ::: "memory");
;         } else {
;             XB_SPIN(xb_ld(&bar[XB_XGEN(b.x)]) == gen, bar);
;             __builtin_amdgcn_fence(__ATOMIC_ACQUIRE, "agent");
;             asm volatile("s_waitcnt vmcnt(0)" ::: "memory");
;         }
;     }
;     __syncthreads();
; }
.LBB0_673:
	s_setprio 0
	s_mov_b32 s2, 0x1c230700
	s_getreg_b32 s4, hwreg(HW_REG_XCC_ID, 0, 4)
	s_waitcnt vmcnt(0)
	s_barrier
	s_and_saveexec_b64 s[0:1], s[82:83]
	s_cbranch_execz .LBB0_725
	v_readlane_b32 s3, v254, 55
	s_waitcnt vmcnt(0) expcnt(0) lgkmcnt(0)
	s_add_u32 s2, s76, s2
	v_mov_b32_e32 v0, s3
	ds_read_b32 v2, v0
	v_readlane_b32 s3, v254, 56
	s_waitcnt lgkmcnt(0)
	v_cmp_ne_u32_e32 vcc, 0, v2
	v_mov_b32_e32 v0, s3
	ds_read_b32 v0, v0
	s_addc_u32 s3, s77, 0
	s_and_b32 s20, s4, 15
	s_cbranch_vccnz .LBB0_689
	s_add_u32 s4, s2, 0x1000
	s_addc_u32 s5, s3, 0
	s_add_u32 s6, s2, 0x1100
	s_addc_u32 s7, s3, 0
	s_add_u32 s8, s2, 0x1200
	s_addc_u32 s9, s3, 0
	s_add_u32 s12, s2, 0x1300
	s_addc_u32 s13, s3, 0
	s_mov_b32 s21, 1
	s_branch .LBB0_677

;   __device__ __forceinline__ bf16* y() const { unsigned o_ = (unsigned)(OFF_y); asm volatile("" : "+s"(o_)); return (bf16*)(ws + o_); }
;   __device__ __forceinline__ bf16* Wb_t() const { unsigned o_ = (unsigned)(OFF_Wb_t); asm volatile("" : "+s"(o_)); return (bf16*)(ws + o_); }
; __device__ void phase_gemm_merge(const P& p, int layer, bf16* lds) {
;     ...
;   uint4 ra0, ra1, ra2, ra3, ra4, ra5, ra6, ra7, rb0, rb1, rb2, rb3, rb4, rb5, rb6, rb7;
;   {
;     int tm, tn; tile_coords(blockIdx.x, NTN, tm, tn, NTM);
;     const bf16* ga = p.y() + (size_t)(tm * 128 + lrow) * D + lcol;
;     const bf16* gb = p.Wb_t() + (size_t)(tn * 128 + lrow) * 256 + lcol;
;     ra0 = *(const uint4*)(ga + (size_t)(16 * 0) * D); ra1 = *(const uint4*)(ga + (size_t)(16 * 1) * D); ra2 = *(const uint4*)(ga + (size_t)(16 * 2) * D); ra3 = *(const uint4*)(ga + (size_t)(16 * 3) * D); ra4 = *(const uint4*)(ga + (size_t)(16 * 4) * D); ra5 = *(const uint4*)(ga + (size_t)(16 * 5) * D); ra6 = *(const uint4*)(ga + (size_t)(16 * 6) * D); ra7 = *(const uint4*)(ga + (size_t)(16 * 7) * D);
;     rb0 = *(const uint4*)(gb + (size_t)(16 * 0) * 256); rb1 = *(const uint4*)(gb + (size_t)(16 * 1) * 256); rb2 = *(const uint4*)(gb + (size_t)(16 * 2) * 256); rb3 = *(const uint4*)(gb + (size_t)(16 * 3) * 256); rb4 = *(const uint4*)(gb + (size_t)(16 * 4) * 256); rb5 = *(const uint4*)(gb + (size_t)(16 * 5) * 256); rb6 = *(const uint4*)(gb + (size_t)(16 * 6) * 256); rb7 = *(const uint4*)(gb + (size_t)(16 * 7) * 256);
;   }
;   __syncthreads();
;   *(uint4*)(As + (lrow + 16 * 0) * LDT + lcol) = ra0; *(uint4*)(As + (lrow + 16 * 1) * LDT + lcol) = ra1; *(uint4*)(As + (lrow + 16 * 2) * LDT + lcol) = ra2; *(uint4*)(As + (lrow + 16 * 3) * LDT + lcol) = ra3; *(uint4*)(As + (lrow + 16 * 4) * LDT + lcol) = ra4; *(uint4*)(As + (lrow + 16 * 5) * LDT + lcol) = ra5; *(uint4*)(As + (lrow + 16 * 6) * LDT + lcol) = ra6; *(uint4*)(As + (lrow + 16 * 7) * LDT + lcol) = ra7;
;   *(uint4*)(Bs + (pbase + 0) * LDT + lcol) = rb0; *(uint4*)(Bs + (pbase + 8) * LDT + lcol) = rb1; *(uint4*)(Bs + (pbase + 32) * LDT + lcol) = rb2; *(uint4*)(Bs + (pbase + 40) * LDT + lcol) = rb3; *(uint4*)(Bs + (pbase + 64) * LDT + lcol) = rb4; *(uint4*)(Bs + (pbase + 72) * LDT + lcol) = rb5; *(uint4*)(Bs + (pbase + 96) * LDT + lcol) = rb6; *(uint4*)(Bs + (pbase + 104) * LDT + lcol) = rb7;
;   __syncthreads();
.LBB0_725:
	s_or_b64 exec, exec, s[0:1]
	v_readlane_b32 s0, v254, 47
	v_readlane_b32 s1, v254, 48
	v_mov_b32_e32 v64, v136
	s_andn2_b64 vcc, exec, s[0:1]
	s_waitcnt lgkmcnt(0)
	s_barrier
	v_readfirstlane_b32 s32, v136
	s_nop 0
	s_cmpk_ge_u32 s32, 0x100
	s_cbranch_scc0 .Lprio_2
	s_setprio 1
.Lprio_2:
	s_cbranch_vccnz .LBB0_734
	v_ashrrev_i32_e32 v170, 5, v64
	v_lshlrev_b32_e32 v0, 3, v64
	s_mov_b32 s0, 0x15603000
	v_readlane_b32 s2, v254, 49
	v_and_b32_e32 v66, 0xf8, v0
	s_add_u32 s0, s76, s0
	v_add_u32_e32 v0, s2, v170
	v_ashrrev_i32_e32 v1, 31, v0
	s_addc_u32 s1, s77, 0
	v_lshlrev_b64 v[0:1], 11, v[0:1]
	v_lshl_add_u64 v[0:1], s[0:1], 0, v[0:1]
	v_lshlrev_b32_e32 v138, 1, v66
	s_mov_b32 s0, 0x19643000
	v_readlane_b32 s2, v254, 50
	v_lshl_add_u64 v[24:25], v[0:1], 0, v[138:139]
	s_add_u32 s0, s76, s0
	v_add_u32_e32 v0, s2, v170
	v_ashrrev_i32_e32 v1, 31, v0
	s_addc_u32 s1, s77, 0
	v_lshlrev_b64 v[0:1], 9, v[0:1]
	v_lshl_add_u64 v[0:1], s[0:1], 0, v[0:1]
	s_mov_b32 s1, 0x8000
	v_lshl_add_u64 v[56:57], v[0:1], 0, v[138:139]
	v_add_co_u32_e32 v0, vcc, s1, v24
	s_mov_b32 s0, 0x28000
	s_nop 0
	v_addc_co_u32_e32 v1, vcc, 0, v25, vcc
	v_add_co_u32_e32 v4, vcc, s46, v24
	v_lshrrev_b32_e32 v67, 3, v64
	s_nop 0
	v_addc_co_u32_e32 v5, vcc, 0, v25, vcc
	v_add_co_u32_e32 v8, vcc, s51, v24
	global_load_dwordx4 v[0:3], v[0:1], off
	s_nop 0
	global_load_dwordx4 v[4:7], v[4:5], off
	v_addc_co_u32_e32 v9, vcc, 0, v25, vcc
	v_add_co_u32_e32 v12, vcc, s56, v24
	v_ashrrev_i32_e32 v69, 6, v64
	s_nop 0
	v_addc_co_u32_e32 v13, vcc, 0, v25, vcc
	v_add_co_u32_e32 v16, vcc, s0, v24
	s_mov_b32 s0, 0x30000
	s_nop 0
	v_addc_co_u32_e32 v17, vcc, 0, v25, vcc
	v_add_co_u32_e32 v20, vcc, s0, v24
	s_mov_b32 s0, 0x38000
	s_nop 0
	v_addc_co_u32_e32 v21, vcc, 0, v25, vcc
	v_add_co_u32_e32 v32, vcc, s0, v24
	s_movk_i32 s0, 0x2000
	s_nop 0
	v_addc_co_u32_e32 v33, vcc, 0, v25, vcc
	v_add_co_u32_e32 v36, vcc, s0, v56
	s_movk_i32 s0, 0x4000
	s_nop 0
	v_addc_co_u32_e32 v37, vcc, 0, v57, vcc
	v_add_co_u32_e32 v40, vcc, s0, v56
	s_movk_i32 s0, 0x6000
	s_nop 0
	v_addc_co_u32_e32 v41, vcc, 0, v57, vcc
	v_add_co_u32_e32 v44, vcc, s0, v56
	s_mov_b32 s0, 0xa000
	s_nop 0
	v_addc_co_u32_e32 v45, vcc, 0, v57, vcc
	v_add_co_u32_e32 v48, vcc, s1, v56
	global_load_dwordx4 v[8:11], v[8:9], off
	s_nop 0
	global_load_dwordx4 v[12:15], v[12:13], off
	v_addc_co_u32_e32 v49, vcc, 0, v57, vcc
	v_add_co_u32_e32 v52, vcc, s0, v56
	s_mov_b32 s0, 0xc000
	s_nop 0
	v_addc_co_u32_e32 v53, vcc, 0, v57, vcc
	v_add_co_u32_e32 v58, vcc, s0, v56
	s_mov_b32 s0, 0xe000
	s_nop 0
	v_addc_co_u32_e32 v59, vcc, 0, v57, vcc
	v_add_co_u32_e32 v60, vcc, s0, v56
	global_load_dwordx4 v[16:19], v[16:17], off
	s_nop 0
	global_load_dwordx4 v[20:23], v[20:21], off
	v_addc_co_u32_e32 v61, vcc, 0, v57, vcc
	global_load_dwordx4 v[24:27], v[24:25], off
	s_nop 0
	global_load_dwordx4 v[28:31], v[56:57], off
	s_nop 0
	global_load_dwordx4 v[32:35], v[32:33], off
	s_nop 0
	global_load_dwordx4 v[36:39], v[36:37], off
	s_nop 0
	global_load_dwordx4 v[40:43], v[40:41], off
	s_nop 0
	global_load_dwordx4 v[44:47], v[44:45], off
	s_nop 0
	global_load_dwordx4 v[48:51], v[48:49], off
	s_nop 0
	global_load_dwordx4 v[52:55], v[52:53], off
	s_nop 0
	global_load_dwordx4 v[56:59], v[58:59], off
	s_nop 0
	global_load_dwordx4 v[60:63], v[60:61], off
	v_and_b32_e32 v67, 16, v67
	v_and_b32_e32 v69, 0xffffffc, v69
	v_add_u32_e32 v67, v67, v69
	v_and_or_b32 v67, v170, 3, v67
	s_movk_i32 s2, 0x210
	v_mul_lo_u32 v67, v67, s2
	v_readlane_b32 s1, v254, 60
	v_and_b32_e32 v65, 15, v64
	v_mul_lo_u32 v69, v170, s2
	v_add3_u32 v172, s1, v67, v138
	v_ashrrev_i32_e32 v67, 2, v64
	s_movk_i32 s0, 0xffe0
	v_add3_u32 v171, s45, v69, v138
	v_lshrrev_b32_e32 v69, 1, v64
	v_and_or_b32 v173, v67, s0, v65
	v_readlane_b32 s0, v254, 61
	v_and_b32_e32 v68, 64, v64
	v_and_b32_e32 v70, 24, v69
	v_and_b32_e32 v64, 0x4f, v64
	s_lshl_b32 s0, s0, 14
	v_readlane_b32 s12, v254, 0
	v_mul_lo_u32 v65, v173, s2
	v_lshlrev_b32_e32 v67, 1, v70
	v_mul_u32_u24_e32 v64, 0x210, v64
	v_readlane_b32 s13, v254, 1
	s_add_u32 s5, s12, s0
	s_mov_b32 s4, 0
	v_add3_u32 v174, s45, v65, v67
	v_add3_u32 v175, s1, v64, v67
	v_or_b32_e32 v176, v70, v68
	s_addc_u32 s6, s13, 0
	v_lshlrev_b32_e32 v138, 1, v68
	v_lshlrev_b32_e32 v116, 1, v70
	v_lshlrev_b32_e32 v118, 1, v66
	s_barrier
	s_waitcnt vmcnt(9)
	ds_write_b128 v171, v[24:27]
	ds_write_b128 v171, v[0:3] offset:8448
	ds_write_b128 v171, v[4:7] offset:16896
	ds_write_b128 v171, v[8:11] offset:25344
	ds_write_b128 v171, v[12:15] offset:33792
	ds_write_b128 v171, v[16:19] offset:42240
	ds_write_b128 v171, v[20:23] offset:50688
	s_waitcnt vmcnt(7)
	ds_write_b128 v171, v[32:35] offset:59136
	ds_write_b128 v172, v[28:31]
	s_waitcnt vmcnt(6)
	ds_write_b128 v172, v[36:39] offset:4224
	s_waitcnt vmcnt(5)
	ds_write_b128 v172, v[40:43] offset:16896
	s_waitcnt vmcnt(4)
	ds_write_b128 v172, v[44:47] offset:21120
	s_waitcnt vmcnt(3)
	ds_write_b128 v172, v[48:51] offset:33792
	s_waitcnt vmcnt(2)
	ds_write_b128 v172, v[52:55] offset:38016
	s_waitcnt vmcnt(1)
	ds_write_b128 v172, v[56:59] offset:50688
	s_waitcnt vmcnt(0)
	ds_write_b128 v172, v[60:63] offset:54912
	s_waitcnt lgkmcnt(0)
	s_barrier
	v_readlane_b32 s14, v254, 2
	v_readlane_b32 s15, v254, 3
	v_readlane_b32 s16, v254, 4
	v_readlane_b32 s17, v254, 5
	v_readlane_b32 s18, v254, 6
	v_readlane_b32 s19, v254, 7
	s_branch .LBB0_728
